# cand2 + nt (streaming) policy on the ffn_in HID stores
# baseline (speedup 1.0000x reference)
; __device__ __forceinline__ unsigned cvt_pk_bf16(float lo, float hi) { unsigned r; asm volatile("v_cvt_pk_bf16_f32 %0, %1, %2" : "=v"(r) : "v"(lo), "v"(hi)); return r; }
;     __device__ __forceinline__ void operator()(const f32x4 (&acc)[2][2][4][2], const Unit& u, int wr, int wc, int fr, int fq) const {
;         const int row0 = u.pm * BM + wr * 64 + fr, col0 = u.pn * HALF + wc * 32 + 8 * fq;
;         const float* cb = cvec + (size_t)((u.pm * BM) / rows_per_batch) * cstride + u.pn * BM + wc * 32 + 8 * fq;
;         long long sv[2][4];
; #pragma unroll
;         for (int ai = 0; ai < 2; ++ai)
; #pragma unroll
;             for (int m = 0; m < 4; ++m) sv[ai][m] = ss[row0 + ai * HALF + m * 16];
;         f32x4 cg0 = *(const f32x4*)(cb), cg1 = *(const f32x4*)(cb + 4), cu0 = *(const f32x4*)(cb + HALF), cu1 = *(const f32x4*)(cb + HALF + 4);
;         asm volatile("" : "+v"(sv[0][0]), "+v"(sv[0][1]), "+v"(sv[0][2]), "+v"(sv[0][3]), "+v"(sv[1][0]), "+v"(sv[1][1]), "+v"(sv[1][2]), "+v"(sv[1][3]), "+v"(cg0), "+v"(cg1), "+v"(cu0), "+v"(cu1));
; #pragma unroll
;         for (int ai = 0; ai < 2; ++ai)
; #pragma unroll
;             for (int m = 0; m < 4; ++m) { bf16_t* rowp = Hd + (size_t)(row0 + ai * HALF + m * 16) * ldh + col0;
;                 const float rstd = __builtin_amdgcn_rsqf((float)sv[ai][m] * (SS_INV * (1.0f / 2048.0f)) + RMS_EPS);
;                 const f32x4 ga = acc[ai][0][m][0] * rstd + cg0, gb = acc[ai][0][m][1] * rstd + cg1, ua = acc[ai][1][m][0] * rstd + cu0, ub = acc[ai][1][m][1] * rstd + cu1;
;                 const f32x4 v0 = fsilu4(ga) * ua, v1 = fsilu4(gb) * ub;
;                 u32x4 w; w.x = cvt_pk_bf16(v0[0], v0[1]); w.y = cvt_pk_bf16(v0[2], v0[3]); w.z = cvt_pk_bf16(v1[0], v1[1]); w.w = cvt_pk_bf16(v1[2], v1[3]);
;                 *(u32x4*)rowp = w; }
.LBB0_637:
	s_ashr_i32 s5, s48, 31
	s_lshr_b32 s5, s5, 27
	s_add_i32 s5, s48, s5
	s_ashr_i32 s5, s5, 5
	s_lshl_b32 s14, s47, 8
	s_ashr_i32 s15, s14, 31
	s_mul_hi_i32 s7, s5, 0xb000
	s_mul_i32 s5, s5, 0xb000
	v_lshl_add_u32 v150, s48, 8, v185
	s_add_u32 s5, s34, s5
	v_or_b32_e32 v194, 16, v150
	s_addc_u32 s7, s35, s7
	s_lshl_b64 s[14:15], s[14:15], 2
	v_ashrrev_i32_e32 v151, 31, v150
	v_ashrrev_i32_e32 v195, 31, v194
	v_or_b32_e32 v180, 32, v150
	s_add_u32 s5, s5, s14
	v_lshl_add_u64 v[82:83], v[150:151], 3, s[42:43]
	v_lshl_add_u64 v[84:85], v[194:195], 3, s[42:43]
	v_ashrrev_i32_e32 v181, 31, v180
	v_or_b32_e32 v160, 48, v150
	s_addc_u32 s7, s7, s15
	global_load_dwordx2 v[182:183], v[84:85], off
	global_load_dwordx2 v[146:147], v[82:83], off offset:1408
	v_lshl_add_u64 v[84:85], v[180:181], 3, s[42:43]
	v_ashrrev_i32_e32 v161, 31, v160
	s_add_u32 s14, s5, s46
	global_load_dwordx2 v[178:179], v[84:85], off
	v_lshl_add_u64 v[84:85], v[160:161], 3, s[42:43]
	s_addc_u32 s15, s7, 0
	global_load_dwordx2 v[192:193], v[82:83], off
	global_load_dwordx2 v[156:157], v[82:83], off offset:1024
	global_load_dwordx2 v[154:155], v[82:83], off offset:1152
	global_load_dwordx2 v[152:153], v[82:83], off offset:1280
	global_load_dwordx2 v[158:159], v[84:85], off
	global_load_dwordx4 v[90:93], v189, s[14:15] offset:16
	global_load_dwordx4 v[94:97], v189, s[14:15]
	s_nop 0
	global_load_dwordx4 v[82:85], v189, s[14:15] offset:528
	global_load_dwordx4 v[86:89], v189, s[14:15] offset:512
	v_readlane_b32 s14, v242, 40
	v_lshl_or_b32 v196, s47, 7, v187
	v_readlane_b32 s15, v242, 41
	v_ashrrev_i32_e32 v197, 31, v196
	s_movk_i32 s5, 0x2c00
	v_mov_b64_e32 v[148:149], s[14:15]
	v_add_u32_e32 v191, 0x80, v150
	v_add_u32_e32 v190, 0x90, v150
	v_add_u32_e32 v181, 0xa0, v150
	v_add_u32_e32 v161, 0xb0, v150
	v_mad_i64_i32 v[198:199], s[14:15], v150, s5, v[148:149]
	v_lshlrev_b64 v[150:151], 1, v[196:197]
	v_lshl_add_u64 v[196:197], v[198:199], 0, v[150:151]
	s_mov_b32 s16, 0xbfb8aa3b
	s_andn2_b64 vcc, exec, s[12:13]
	s_movk_i32 s49, 0x3000
	v_readlane_b32 s50, v241, 17
	s_mov_b32 s51, 0xd800000
	s_waitcnt vmcnt(0)
	s_nop 0
	v_xor_b32_e32 v195, v192, v193
	v_ashrrev_i32_e32 v195, 31, v195
	v_ffbh_i32_e32 v198, v193
	v_add_u32_e32 v195, 32, v195
	v_add_u32_e32 v198, -1, v198
	v_min_u32_e32 v195, v198, v195
	v_lshlrev_b64 v[192:193], v195, v[192:193]
	v_min_u32_e32 v192, 1, v192
	v_or_b32_e32 v192, v193, v192
	v_cvt_f32_i32_e32 v192, v192
	v_sub_u32_e32 v193, 32, v195
	v_ldexp_f32 v192, v192, v193
	v_fmamk_f32 v192, v192, 0x32000000, v216
	v_rsq_f32_e32 v192, v192
	s_nop 0
	v_pk_fma_f32 v[142:143], v[142:143], v[192:193], v[94:95] op_sel_hi:[1,0,1]
	v_pk_fma_f32 v[144:145], v[144:145], v[192:193], v[96:97] op_sel_hi:[1,0,1]
	v_pk_fma_f32 v[138:139], v[138:139], v[192:193], v[90:91] op_sel_hi:[1,0,1]
	v_pk_fma_f32 v[140:141], v[140:141], v[192:193], v[92:93] op_sel_hi:[1,0,1]
	v_pk_fma_f32 v[134:135], v[134:135], v[192:193], v[86:87] op_sel_hi:[1,0,1]
	v_pk_fma_f32 v[136:137], v[136:137], v[192:193], v[88:89] op_sel_hi:[1,0,1]
	v_pk_fma_f32 v[130:131], v[130:131], v[192:193], v[82:83] op_sel_hi:[1,0,1]
	v_pk_fma_f32 v[132:133], v[132:133], v[192:193], v[84:85] op_sel_hi:[1,0,1]
	v_pk_mul_f32 v[192:193], v[144:145], s[16:17] op_sel_hi:[1,0]
	v_pk_mul_f32 v[198:199], v[142:143], s[16:17] op_sel_hi:[1,0]
	v_exp_f32_e32 v192, v192
	v_exp_f32_e32 v198, v198
	v_exp_f32_e32 v199, v199
	v_exp_f32_e32 v193, v193
	v_pk_add_f32 v[198:199], v[198:199], 1.0 op_sel_hi:[1,0]
	v_pk_add_f32 v[192:193], v[192:193], 1.0 op_sel_hi:[1,0]
	v_rcp_f32_e32 v198, v198
	v_rcp_f32_e32 v199, v199
	v_rcp_f32_e32 v192, v192
	v_rcp_f32_e32 v193, v193
	v_pk_mul_f32 v[142:143], v[142:143], v[198:199]
	s_nop 0
	v_pk_mul_f32 v[134:135], v[134:135], v[142:143]
	v_pk_mul_f32 v[144:145], v[144:145], v[192:193]
	v_pk_mul_f32 v[142:143], v[140:141], s[16:17] op_sel_hi:[1,0]
	v_pk_mul_f32 v[136:137], v[136:137], v[144:145]
	v_pk_mul_f32 v[144:145], v[138:139], s[16:17] op_sel_hi:[1,0]
	v_exp_f32_e32 v142, v142
	v_exp_f32_e32 v144, v144
	v_exp_f32_e32 v145, v145
	v_exp_f32_e32 v143, v143
	v_pk_add_f32 v[144:145], v[144:145], 1.0 op_sel_hi:[1,0]
	v_pk_add_f32 v[142:143], v[142:143], 1.0 op_sel_hi:[1,0]
	v_rcp_f32_e32 v144, v144
	v_rcp_f32_e32 v145, v145
	v_rcp_f32_e32 v142, v142
	v_rcp_f32_e32 v143, v143
	v_pk_mul_f32 v[138:139], v[138:139], v[144:145]
	v_pk_mul_f32 v[140:141], v[140:141], v[142:143]
	s_nop 0
	v_pk_mul_f32 v[140:141], v[132:133], v[140:141]
	v_pk_mul_f32 v[132:133], v[130:131], v[138:139]
	v_cvt_pk_bf16_f32 v130, v134, v135
	v_cvt_pk_bf16_f32 v131, v136, v137
	s_nop 0
	v_cvt_pk_bf16_f32 v132, v132, v133
	v_cvt_pk_bf16_f32 v133, v140, v141
	global_store_dwordx4 v[196:197], v[130:133], off nt
	s_nop 1
	v_xor_b32_e32 v132, v182, v183
	v_ashrrev_i32_e32 v132, 31, v132
	v_ffbh_i32_e32 v133, v183
	v_add_u32_e32 v132, 32, v132
	v_add_u32_e32 v133, -1, v133
	v_min_u32_e32 v134, v133, v132
	v_lshlrev_b64 v[132:133], v134, v[182:183]
	v_min_u32_e32 v132, 1, v132
	v_or_b32_e32 v132, v133, v132
	v_cvt_f32_i32_e32 v132, v132
	v_sub_u32_e32 v133, 32, v134
	v_mad_i64_i32 v[130:131], s[14:15], v194, s5, v[148:149]
	v_ldexp_f32 v132, v132, v133
	v_fmamk_f32 v132, v132, 0x32000000, v216
	v_rsq_f32_e32 v132, v132
	v_lshl_add_u64 v[130:131], v[130:131], 0, v[150:151]
	v_pk_fma_f32 v[126:127], v[126:127], v[132:133], v[94:95] op_sel_hi:[1,0,1]
	v_pk_fma_f32 v[128:129], v[128:129], v[132:133], v[96:97] op_sel_hi:[1,0,1]
	v_pk_fma_f32 v[122:123], v[122:123], v[132:133], v[90:91] op_sel_hi:[1,0,1]
	v_pk_fma_f32 v[124:125], v[124:125], v[132:133], v[92:93] op_sel_hi:[1,0,1]
	v_pk_fma_f32 v[118:119], v[118:119], v[132:133], v[86:87] op_sel_hi:[1,0,1]
; __device__ __forceinline__ unsigned cvt_pk_bf16(float lo, float hi) { unsigned r; asm volatile("v_cvt_pk_bf16_f32 %0, %1, %2" : "=v"(r) : "v"(lo), "v"(hi)); return r; }
;     __device__ __forceinline__ void operator()(const f32x4 (&acc)[2][2][4][2], const Unit& u, int wr, int wc, int fr, int fq) const {
;     ...
;             for (int m = 0; m < 4; ++m) { bf16_t* rowp = Hd + (size_t)(row0 + ai * HALF + m * 16) * ldh + col0;
;                 const float rstd = __builtin_amdgcn_rsqf((float)sv[ai][m] * (SS_INV * (1.0f / 2048.0f)) + RMS_EPS);
;                 const f32x4 ga = acc[ai][0][m][0] * rstd + cg0, gb = acc[ai][0][m][1] * rstd + cg1, ua = acc[ai][1][m][0] * rstd + cu0, ub = acc[ai][1][m][1] * rstd + cu1;
;                 const f32x4 v0 = fsilu4(ga) * ua, v1 = fsilu4(gb) * ub;
;                 u32x4 w; w.x = cvt_pk_bf16(v0[0], v0[1]); w.y = cvt_pk_bf16(v0[2], v0[3]); w.z = cvt_pk_bf16(v1[0], v1[1]); w.w = cvt_pk_bf16(v1[2], v1[3]);
;                 *(u32x4*)rowp = w; }
	v_pk_fma_f32 v[120:121], v[120:121], v[132:133], v[88:89] op_sel_hi:[1,0,1]
	v_pk_fma_f32 v[114:115], v[114:115], v[132:133], v[82:83] op_sel_hi:[1,0,1]
	v_pk_fma_f32 v[116:117], v[116:117], v[132:133], v[84:85] op_sel_hi:[1,0,1]
	v_pk_mul_f32 v[132:133], v[128:129], s[16:17] op_sel_hi:[1,0]
	v_pk_mul_f32 v[134:135], v[126:127], s[16:17] op_sel_hi:[1,0]
	v_exp_f32_e32 v132, v132
	v_exp_f32_e32 v134, v134
	v_exp_f32_e32 v135, v135
	v_exp_f32_e32 v133, v133
	v_pk_add_f32 v[134:135], v[134:135], 1.0 op_sel_hi:[1,0]
	v_pk_add_f32 v[132:133], v[132:133], 1.0 op_sel_hi:[1,0]
	v_rcp_f32_e32 v134, v134
	v_rcp_f32_e32 v135, v135
	v_rcp_f32_e32 v132, v132
	v_rcp_f32_e32 v133, v133
	v_pk_mul_f32 v[126:127], v[126:127], v[134:135]
	s_nop 0
	v_pk_mul_f32 v[118:119], v[118:119], v[126:127]
	v_pk_mul_f32 v[128:129], v[128:129], v[132:133]
	v_pk_mul_f32 v[126:127], v[124:125], s[16:17] op_sel_hi:[1,0]
	v_pk_mul_f32 v[120:121], v[120:121], v[128:129]
	v_pk_mul_f32 v[128:129], v[122:123], s[16:17] op_sel_hi:[1,0]
	v_exp_f32_e32 v126, v126
	v_exp_f32_e32 v128, v128
	v_exp_f32_e32 v129, v129
	v_exp_f32_e32 v127, v127
	v_pk_add_f32 v[128:129], v[128:129], 1.0 op_sel_hi:[1,0]
	v_pk_add_f32 v[126:127], v[126:127], 1.0 op_sel_hi:[1,0]
	v_rcp_f32_e32 v128, v128
	v_rcp_f32_e32 v129, v129
	v_rcp_f32_e32 v126, v126
	v_rcp_f32_e32 v127, v127
	v_pk_mul_f32 v[122:123], v[122:123], v[128:129]
	v_pk_mul_f32 v[124:125], v[124:125], v[126:127]
	s_nop 0
	v_pk_mul_f32 v[124:125], v[116:117], v[124:125]
	v_pk_mul_f32 v[116:117], v[114:115], v[122:123]
	v_cvt_pk_bf16_f32 v114, v118, v119
	v_cvt_pk_bf16_f32 v115, v120, v121
	s_nop 0
	v_cvt_pk_bf16_f32 v116, v116, v117
	v_cvt_pk_bf16_f32 v117, v124, v125
	global_store_dwordx4 v[130:131], v[114:117], off nt
	s_nop 1
	v_xor_b32_e32 v116, v178, v179
	v_ashrrev_i32_e32 v116, 31, v116
	v_ffbh_i32_e32 v117, v179
	v_add_u32_e32 v116, 32, v116
	v_add_u32_e32 v117, -1, v117
	v_min_u32_e32 v118, v117, v116
	v_lshlrev_b64 v[116:117], v118, v[178:179]
	v_min_u32_e32 v116, 1, v116
	v_or_b32_e32 v116, v117, v116
	v_cvt_f32_i32_e32 v116, v116
	v_sub_u32_e32 v117, 32, v118
	v_mad_i64_i32 v[114:115], s[14:15], v180, s5, v[148:149]
	v_ldexp_f32 v116, v116, v117
	v_fmamk_f32 v116, v116, 0x32000000, v216
	v_rsq_f32_e32 v116, v116
	v_lshl_add_u64 v[114:115], v[114:115], 0, v[150:151]
	v_pk_fma_f32 v[110:111], v[110:111], v[116:117], v[94:95] op_sel_hi:[1,0,1]
	v_pk_fma_f32 v[112:113], v[112:113], v[116:117], v[96:97] op_sel_hi:[1,0,1]
	v_pk_fma_f32 v[106:107], v[106:107], v[116:117], v[90:91] op_sel_hi:[1,0,1]
	v_pk_fma_f32 v[108:109], v[108:109], v[116:117], v[92:93] op_sel_hi:[1,0,1]
	v_pk_fma_f32 v[102:103], v[102:103], v[116:117], v[86:87] op_sel_hi:[1,0,1]
	v_pk_fma_f32 v[104:105], v[104:105], v[116:117], v[88:89] op_sel_hi:[1,0,1]
	v_pk_fma_f32 v[98:99], v[98:99], v[116:117], v[82:83] op_sel_hi:[1,0,1]
	v_pk_fma_f32 v[100:101], v[100:101], v[116:117], v[84:85] op_sel_hi:[1,0,1]
	v_pk_mul_f32 v[116:117], v[112:113], s[16:17] op_sel_hi:[1,0]
	v_pk_mul_f32 v[118:119], v[110:111], s[16:17] op_sel_hi:[1,0]
	v_exp_f32_e32 v116, v116
	v_exp_f32_e32 v118, v118
	v_exp_f32_e32 v119, v119
	v_exp_f32_e32 v117, v117
	v_pk_add_f32 v[118:119], v[118:119], 1.0 op_sel_hi:[1,0]
	v_pk_add_f32 v[116:117], v[116:117], 1.0 op_sel_hi:[1,0]
	v_rcp_f32_e32 v118, v118
	v_rcp_f32_e32 v119, v119
	v_rcp_f32_e32 v116, v116
	v_rcp_f32_e32 v117, v117
	v_pk_mul_f32 v[110:111], v[110:111], v[118:119]
	s_nop 0
	v_pk_mul_f32 v[102:103], v[102:103], v[110:111]
	v_pk_mul_f32 v[112:113], v[112:113], v[116:117]
	v_pk_mul_f32 v[110:111], v[108:109], s[16:17] op_sel_hi:[1,0]
	v_pk_mul_f32 v[104:105], v[104:105], v[112:113]
	v_pk_mul_f32 v[112:113], v[106:107], s[16:17] op_sel_hi:[1,0]
	v_exp_f32_e32 v110, v110
	v_exp_f32_e32 v112, v112
	v_exp_f32_e32 v113, v113
	v_exp_f32_e32 v111, v111
	v_pk_add_f32 v[112:113], v[112:113], 1.0 op_sel_hi:[1,0]
	v_pk_add_f32 v[110:111], v[110:111], 1.0 op_sel_hi:[1,0]
	v_rcp_f32_e32 v112, v112
	v_rcp_f32_e32 v113, v113
	v_rcp_f32_e32 v110, v110
	v_rcp_f32_e32 v111, v111
	v_pk_mul_f32 v[106:107], v[106:107], v[112:113]
	v_pk_mul_f32 v[108:109], v[108:109], v[110:111]
	s_nop 0
	v_pk_mul_f32 v[108:109], v[100:101], v[108:109]
	v_pk_mul_f32 v[100:101], v[98:99], v[106:107]
	v_cvt_pk_bf16_f32 v98, v102, v103
	v_cvt_pk_bf16_f32 v99, v104, v105
	s_nop 0
	v_cvt_pk_bf16_f32 v100, v100, v101
	v_cvt_pk_bf16_f32 v101, v108, v109
	global_store_dwordx4 v[114:115], v[98:101], off nt
	s_nop 1
	v_xor_b32_e32 v100, v158, v159
	v_ashrrev_i32_e32 v100, 31, v100
	v_ffbh_i32_e32 v101, v159
	v_add_u32_e32 v100, 32, v100
	v_add_u32_e32 v101, -1, v101
	v_min_u32_e32 v102, v101, v100
	v_lshlrev_b64 v[100:101], v102, v[158:159]
	v_min_u32_e32 v100, 1, v100
	v_or_b32_e32 v100, v101, v100
	v_cvt_f32_i32_e32 v100, v100
	v_sub_u32_e32 v101, 32, v102
	v_mad_i64_i32 v[98:99], s[14:15], v160, s5, v[148:149]
	v_ldexp_f32 v100, v100, v101
	v_fmamk_f32 v100, v100, 0x32000000, v216
	v_rsq_f32_e32 v100, v100
	v_lshl_add_u64 v[98:99], v[98:99], 0, v[150:151]
	v_pk_fma_f32 v[78:79], v[78:79], v[100:101], v[94:95] op_sel_hi:[1,0,1]
	v_pk_fma_f32 v[80:81], v[80:81], v[100:101], v[96:97] op_sel_hi:[1,0,1]
	v_pk_fma_f32 v[74:75], v[74:75], v[100:101], v[90:91] op_sel_hi:[1,0,1]
	v_pk_fma_f32 v[76:77], v[76:77], v[100:101], v[92:93] op_sel_hi:[1,0,1]
	v_pk_fma_f32 v[70:71], v[70:71], v[100:101], v[86:87] op_sel_hi:[1,0,1]
	v_pk_fma_f32 v[72:73], v[72:73], v[100:101], v[88:89] op_sel_hi:[1,0,1]
	v_pk_fma_f32 v[66:67], v[66:67], v[100:101], v[82:83] op_sel_hi:[1,0,1]
	v_pk_fma_f32 v[68:69], v[68:69], v[100:101], v[84:85] op_sel_hi:[1,0,1]
	v_pk_mul_f32 v[100:101], v[80:81], s[16:17] op_sel_hi:[1,0]
; __device__ __forceinline__ unsigned cvt_pk_bf16(float lo, float hi) { unsigned r; asm volatile("v_cvt_pk_bf16_f32 %0, %1, %2" : "=v"(r) : "v"(lo), "v"(hi)); return r; }
;     __device__ __forceinline__ void operator()(const f32x4 (&acc)[2][2][4][2], const Unit& u, int wr, int wc, int fr, int fq) const {
;     ...
;             for (int m = 0; m < 4; ++m) { bf16_t* rowp = Hd + (size_t)(row0 + ai * HALF + m * 16) * ldh + col0;
;                 const float rstd = __builtin_amdgcn_rsqf((float)sv[ai][m] * (SS_INV * (1.0f / 2048.0f)) + RMS_EPS);
;                 const f32x4 ga = acc[ai][0][m][0] * rstd + cg0, gb = acc[ai][0][m][1] * rstd + cg1, ua = acc[ai][1][m][0] * rstd + cu0, ub = acc[ai][1][m][1] * rstd + cu1;
;                 const f32x4 v0 = fsilu4(ga) * ua, v1 = fsilu4(gb) * ub;
;                 u32x4 w; w.x = cvt_pk_bf16(v0[0], v0[1]); w.y = cvt_pk_bf16(v0[2], v0[3]); w.z = cvt_pk_bf16(v1[0], v1[1]); w.w = cvt_pk_bf16(v1[2], v1[3]);
;                 *(u32x4*)rowp = w; }
	v_pk_mul_f32 v[102:103], v[78:79], s[16:17] op_sel_hi:[1,0]
	v_exp_f32_e32 v100, v100
	v_exp_f32_e32 v102, v102
	v_exp_f32_e32 v103, v103
	v_exp_f32_e32 v101, v101
	v_pk_add_f32 v[102:103], v[102:103], 1.0 op_sel_hi:[1,0]
	v_pk_add_f32 v[100:101], v[100:101], 1.0 op_sel_hi:[1,0]
	v_rcp_f32_e32 v102, v102
	v_rcp_f32_e32 v103, v103
	v_rcp_f32_e32 v100, v100
	v_rcp_f32_e32 v101, v101
	v_pk_mul_f32 v[78:79], v[78:79], v[102:103]
	s_nop 0
	v_pk_mul_f32 v[70:71], v[70:71], v[78:79]
	v_pk_mul_f32 v[80:81], v[80:81], v[100:101]
	v_pk_mul_f32 v[78:79], v[76:77], s[16:17] op_sel_hi:[1,0]
	v_pk_mul_f32 v[72:73], v[72:73], v[80:81]
	v_pk_mul_f32 v[80:81], v[74:75], s[16:17] op_sel_hi:[1,0]
	v_exp_f32_e32 v78, v78
	v_exp_f32_e32 v80, v80
	v_exp_f32_e32 v81, v81
	v_exp_f32_e32 v79, v79
	v_pk_add_f32 v[80:81], v[80:81], 1.0 op_sel_hi:[1,0]
	v_pk_add_f32 v[78:79], v[78:79], 1.0 op_sel_hi:[1,0]
	v_rcp_f32_e32 v80, v80
	v_rcp_f32_e32 v81, v81
	v_rcp_f32_e32 v78, v78
	v_rcp_f32_e32 v79, v79
	v_pk_mul_f32 v[74:75], v[74:75], v[80:81]
	v_pk_mul_f32 v[76:77], v[76:77], v[78:79]
	s_nop 0
	v_pk_mul_f32 v[76:77], v[68:69], v[76:77]
	v_pk_mul_f32 v[68:69], v[66:67], v[74:75]
	v_cvt_pk_bf16_f32 v66, v70, v71
	v_cvt_pk_bf16_f32 v67, v72, v73
	s_nop 0
	v_cvt_pk_bf16_f32 v68, v68, v69
	v_cvt_pk_bf16_f32 v69, v76, v77
	global_store_dwordx4 v[98:99], v[66:69], off nt
	s_nop 1
	v_xor_b32_e32 v68, v156, v157
	v_ashrrev_i32_e32 v68, 31, v68
	v_ffbh_i32_e32 v69, v157
	v_add_u32_e32 v68, 32, v68
	v_add_u32_e32 v69, -1, v69
	v_min_u32_e32 v70, v69, v68
	v_lshlrev_b64 v[68:69], v70, v[156:157]
	v_min_u32_e32 v68, 1, v68
	v_or_b32_e32 v68, v69, v68
	v_cvt_f32_i32_e32 v68, v68
	v_sub_u32_e32 v69, 32, v70
	v_mad_i64_i32 v[66:67], s[14:15], v191, s5, v[148:149]
	v_ldexp_f32 v68, v68, v69
	v_fmamk_f32 v68, v68, 0x32000000, v216
	v_rsq_f32_e32 v68, v68
	v_lshl_add_u64 v[66:67], v[66:67], 0, v[150:151]
	v_pk_fma_f32 v[62:63], v[62:63], v[68:69], v[94:95] op_sel_hi:[1,0,1]
	v_pk_fma_f32 v[64:65], v[64:65], v[68:69], v[96:97] op_sel_hi:[1,0,1]
	v_pk_fma_f32 v[58:59], v[58:59], v[68:69], v[90:91] op_sel_hi:[1,0,1]
	v_pk_fma_f32 v[60:61], v[60:61], v[68:69], v[92:93] op_sel_hi:[1,0,1]
	v_pk_fma_f32 v[54:55], v[54:55], v[68:69], v[86:87] op_sel_hi:[1,0,1]
	v_pk_fma_f32 v[56:57], v[56:57], v[68:69], v[88:89] op_sel_hi:[1,0,1]
	v_pk_fma_f32 v[50:51], v[50:51], v[68:69], v[82:83] op_sel_hi:[1,0,1]
	v_pk_fma_f32 v[52:53], v[52:53], v[68:69], v[84:85] op_sel_hi:[1,0,1]
	v_pk_mul_f32 v[68:69], v[64:65], s[16:17] op_sel_hi:[1,0]
	v_pk_mul_f32 v[70:71], v[62:63], s[16:17] op_sel_hi:[1,0]
	v_exp_f32_e32 v68, v68
	v_exp_f32_e32 v70, v70
	v_exp_f32_e32 v71, v71
	v_exp_f32_e32 v69, v69
	v_pk_add_f32 v[70:71], v[70:71], 1.0 op_sel_hi:[1,0]
	v_pk_add_f32 v[68:69], v[68:69], 1.0 op_sel_hi:[1,0]
	v_rcp_f32_e32 v70, v70
	v_rcp_f32_e32 v71, v71
	v_rcp_f32_e32 v68, v68
	v_rcp_f32_e32 v69, v69
	v_pk_mul_f32 v[62:63], v[62:63], v[70:71]
	s_nop 0
	v_pk_mul_f32 v[54:55], v[54:55], v[62:63]
	v_pk_mul_f32 v[64:65], v[64:65], v[68:69]
	v_pk_mul_f32 v[62:63], v[60:61], s[16:17] op_sel_hi:[1,0]
	v_pk_mul_f32 v[56:57], v[56:57], v[64:65]
	v_pk_mul_f32 v[64:65], v[58:59], s[16:17] op_sel_hi:[1,0]
	v_exp_f32_e32 v62, v62
	v_exp_f32_e32 v64, v64
	v_exp_f32_e32 v65, v65
	v_exp_f32_e32 v63, v63
	v_pk_add_f32 v[64:65], v[64:65], 1.0 op_sel_hi:[1,0]
	v_pk_add_f32 v[62:63], v[62:63], 1.0 op_sel_hi:[1,0]
	v_rcp_f32_e32 v64, v64
	v_rcp_f32_e32 v65, v65
	v_rcp_f32_e32 v62, v62
	v_rcp_f32_e32 v63, v63
	v_pk_mul_f32 v[58:59], v[58:59], v[64:65]
	v_pk_mul_f32 v[60:61], v[60:61], v[62:63]
	s_nop 0
	v_pk_mul_f32 v[60:61], v[52:53], v[60:61]
	v_pk_mul_f32 v[52:53], v[50:51], v[58:59]
	v_cvt_pk_bf16_f32 v50, v54, v55
	v_cvt_pk_bf16_f32 v51, v56, v57
	s_nop 0
	v_cvt_pk_bf16_f32 v52, v52, v53
	v_cvt_pk_bf16_f32 v53, v60, v61
	global_store_dwordx4 v[66:67], v[50:53], off nt
	s_nop 1
	v_xor_b32_e32 v52, v154, v155
	v_ashrrev_i32_e32 v52, 31, v52
	v_ffbh_i32_e32 v53, v155
	v_add_u32_e32 v52, 32, v52
	v_add_u32_e32 v53, -1, v53
	v_min_u32_e32 v54, v53, v52
	v_lshlrev_b64 v[52:53], v54, v[154:155]
	v_min_u32_e32 v52, 1, v52
	v_or_b32_e32 v52, v53, v52
	v_cvt_f32_i32_e32 v52, v52
	v_sub_u32_e32 v53, 32, v54
	v_mad_i64_i32 v[50:51], s[14:15], v190, s5, v[148:149]
	v_ldexp_f32 v52, v52, v53
	v_fmamk_f32 v52, v52, 0x32000000, v216
	v_rsq_f32_e32 v52, v52
	v_lshl_add_u64 v[50:51], v[50:51], 0, v[150:151]
	v_pk_fma_f32 v[46:47], v[46:47], v[52:53], v[94:95] op_sel_hi:[1,0,1]
	v_pk_fma_f32 v[48:49], v[48:49], v[52:53], v[96:97] op_sel_hi:[1,0,1]
	v_pk_fma_f32 v[42:43], v[42:43], v[52:53], v[90:91] op_sel_hi:[1,0,1]
	v_pk_fma_f32 v[44:45], v[44:45], v[52:53], v[92:93] op_sel_hi:[1,0,1]
	v_pk_fma_f32 v[38:39], v[38:39], v[52:53], v[86:87] op_sel_hi:[1,0,1]
	v_pk_fma_f32 v[40:41], v[40:41], v[52:53], v[88:89] op_sel_hi:[1,0,1]
	v_pk_fma_f32 v[34:35], v[34:35], v[52:53], v[82:83] op_sel_hi:[1,0,1]
	v_pk_fma_f32 v[36:37], v[36:37], v[52:53], v[84:85] op_sel_hi:[1,0,1]
	v_pk_mul_f32 v[52:53], v[48:49], s[16:17] op_sel_hi:[1,0]
	v_pk_mul_f32 v[54:55], v[46:47], s[16:17] op_sel_hi:[1,0]
	v_exp_f32_e32 v52, v52
	v_exp_f32_e32 v54, v54
	v_exp_f32_e32 v55, v55
	v_exp_f32_e32 v53, v53
	v_pk_add_f32 v[54:55], v[54:55], 1.0 op_sel_hi:[1,0]
	v_pk_add_f32 v[52:53], v[52:53], 1.0 op_sel_hi:[1,0]
	v_rcp_f32_e32 v54, v54
	v_rcp_f32_e32 v55, v55
	v_rcp_f32_e32 v52, v52
	v_rcp_f32_e32 v53, v53
	v_pk_mul_f32 v[46:47], v[46:47], v[54:55]
	s_nop 0
	v_pk_mul_f32 v[38:39], v[38:39], v[46:47]
	v_pk_mul_f32 v[48:49], v[48:49], v[52:53]
	v_pk_mul_f32 v[46:47], v[44:45], s[16:17] op_sel_hi:[1,0]
	v_pk_mul_f32 v[40:41], v[40:41], v[48:49]
	v_pk_mul_f32 v[48:49], v[42:43], s[16:17] op_sel_hi:[1,0]
; __device__ __forceinline__ unsigned cvt_pk_bf16(float lo, float hi) { unsigned r; asm volatile("v_cvt_pk_bf16_f32 %0, %1, %2" : "=v"(r) : "v"(lo), "v"(hi)); return r; }
; #define PG8_BAR __builtin_amdgcn_s_barrier()
;     __device__ __forceinline__ void operator()(const f32x4 (&acc)[2][2][4][2], const Unit& u, int wr, int wc, int fr, int fq) const {
;     ...
;             for (int m = 0; m < 4; ++m) { bf16_t* rowp = Hd + (size_t)(row0 + ai * HALF + m * 16) * ldh + col0;
;                 const float rstd = __builtin_amdgcn_rsqf((float)sv[ai][m] * (SS_INV * (1.0f / 2048.0f)) + RMS_EPS);
;                 const f32x4 ga = acc[ai][0][m][0] * rstd + cg0, gb = acc[ai][0][m][1] * rstd + cg1, ua = acc[ai][1][m][0] * rstd + cu0, ub = acc[ai][1][m][1] * rstd + cu1;
;                 const f32x4 v0 = fsilu4(ga) * ua, v1 = fsilu4(gb) * ub;
;                 u32x4 w; w.x = cvt_pk_bf16(v0[0], v0[1]); w.y = cvt_pk_bf16(v0[2], v0[3]); w.z = cvt_pk_bf16(v1[0], v1[1]); w.w = cvt_pk_bf16(v1[2], v1[3]);
;                 *(u32x4*)rowp = w; }
; template <class Epi, class Sched, bool ALIGN_EPI = false, bool SP2 = false>
; __device__ __forceinline__ void gemm_phase(PG8_LAS unsigned char* lds, const Gemm g, const Sched& S, const Epi& E) {
;     ...
;         cur = nxt; cA = nA; cB = nB; ++ui;
;         if constexpr (ALIGN_EPI) { if (wr == 1) PG8_BAR; }
	v_exp_f32_e32 v46, v46
	v_exp_f32_e32 v48, v48
	v_exp_f32_e32 v49, v49
	v_exp_f32_e32 v47, v47
	v_pk_add_f32 v[48:49], v[48:49], 1.0 op_sel_hi:[1,0]
	v_pk_add_f32 v[46:47], v[46:47], 1.0 op_sel_hi:[1,0]
	v_rcp_f32_e32 v48, v48
	v_rcp_f32_e32 v49, v49
	v_rcp_f32_e32 v46, v46
	v_rcp_f32_e32 v47, v47
	v_pk_mul_f32 v[42:43], v[42:43], v[48:49]
	v_pk_mul_f32 v[44:45], v[44:45], v[46:47]
	s_nop 0
	v_pk_mul_f32 v[44:45], v[36:37], v[44:45]
	v_pk_mul_f32 v[36:37], v[34:35], v[42:43]
	v_cvt_pk_bf16_f32 v34, v38, v39
	v_cvt_pk_bf16_f32 v35, v40, v41
	s_nop 0
	v_cvt_pk_bf16_f32 v36, v36, v37
	v_cvt_pk_bf16_f32 v37, v44, v45
	global_store_dwordx4 v[50:51], v[34:37], off nt
	s_nop 1
	v_xor_b32_e32 v36, v152, v153
	v_ashrrev_i32_e32 v36, 31, v36
	v_ffbh_i32_e32 v37, v153
	v_add_u32_e32 v36, 32, v36
	v_add_u32_e32 v37, -1, v37
	v_min_u32_e32 v38, v37, v36
	v_lshlrev_b64 v[36:37], v38, v[152:153]
	v_min_u32_e32 v36, 1, v36
	v_or_b32_e32 v36, v37, v36
	v_cvt_f32_i32_e32 v36, v36
	v_sub_u32_e32 v37, 32, v38
	v_mad_i64_i32 v[34:35], s[14:15], v181, s5, v[148:149]
	v_ldexp_f32 v36, v36, v37
	v_fmamk_f32 v36, v36, 0x32000000, v216
	v_rsq_f32_e32 v36, v36
	v_lshl_add_u64 v[34:35], v[34:35], 0, v[150:151]
	v_pk_fma_f32 v[30:31], v[30:31], v[36:37], v[94:95] op_sel_hi:[1,0,1]
	v_pk_fma_f32 v[32:33], v[32:33], v[36:37], v[96:97] op_sel_hi:[1,0,1]
	v_pk_fma_f32 v[26:27], v[26:27], v[36:37], v[90:91] op_sel_hi:[1,0,1]
	v_pk_fma_f32 v[28:29], v[28:29], v[36:37], v[92:93] op_sel_hi:[1,0,1]
	v_pk_fma_f32 v[22:23], v[22:23], v[36:37], v[86:87] op_sel_hi:[1,0,1]
	v_pk_fma_f32 v[24:25], v[24:25], v[36:37], v[88:89] op_sel_hi:[1,0,1]
	v_pk_fma_f32 v[18:19], v[18:19], v[36:37], v[82:83] op_sel_hi:[1,0,1]
	v_pk_fma_f32 v[20:21], v[20:21], v[36:37], v[84:85] op_sel_hi:[1,0,1]
	v_pk_mul_f32 v[36:37], v[32:33], s[16:17] op_sel_hi:[1,0]
	v_pk_mul_f32 v[38:39], v[30:31], s[16:17] op_sel_hi:[1,0]
	v_exp_f32_e32 v36, v36
	v_exp_f32_e32 v38, v38
	v_exp_f32_e32 v39, v39
	v_exp_f32_e32 v37, v37
	v_pk_add_f32 v[38:39], v[38:39], 1.0 op_sel_hi:[1,0]
	v_pk_add_f32 v[36:37], v[36:37], 1.0 op_sel_hi:[1,0]
	v_rcp_f32_e32 v38, v38
	v_rcp_f32_e32 v39, v39
	v_rcp_f32_e32 v36, v36
	v_rcp_f32_e32 v37, v37
	v_pk_mul_f32 v[30:31], v[30:31], v[38:39]
	s_nop 0
	v_pk_mul_f32 v[22:23], v[22:23], v[30:31]
	v_pk_mul_f32 v[32:33], v[32:33], v[36:37]
	v_pk_mul_f32 v[30:31], v[28:29], s[16:17] op_sel_hi:[1,0]
	v_pk_mul_f32 v[24:25], v[24:25], v[32:33]
	v_pk_mul_f32 v[32:33], v[26:27], s[16:17] op_sel_hi:[1,0]
	v_exp_f32_e32 v30, v30
	v_exp_f32_e32 v32, v32
	v_exp_f32_e32 v33, v33
	v_exp_f32_e32 v31, v31
	v_pk_add_f32 v[32:33], v[32:33], 1.0 op_sel_hi:[1,0]
	v_pk_add_f32 v[30:31], v[30:31], 1.0 op_sel_hi:[1,0]
	v_rcp_f32_e32 v32, v32
	v_rcp_f32_e32 v33, v33
	v_rcp_f32_e32 v30, v30
	v_rcp_f32_e32 v31, v31
	v_pk_mul_f32 v[26:27], v[26:27], v[32:33]
	v_pk_mul_f32 v[28:29], v[28:29], v[30:31]
	s_nop 0
	v_pk_mul_f32 v[28:29], v[20:21], v[28:29]
	v_pk_mul_f32 v[20:21], v[18:19], v[26:27]
	v_cvt_pk_bf16_f32 v18, v22, v23
	v_cvt_pk_bf16_f32 v19, v24, v25
	s_nop 0
	v_cvt_pk_bf16_f32 v20, v20, v21
	v_cvt_pk_bf16_f32 v21, v28, v29
	global_store_dwordx4 v[34:35], v[18:21], off nt
	s_nop 1
	v_xor_b32_e32 v20, v146, v147
	v_ashrrev_i32_e32 v20, 31, v20
	v_ffbh_i32_e32 v21, v147
	v_add_u32_e32 v20, 32, v20
	v_add_u32_e32 v21, -1, v21
	v_min_u32_e32 v22, v21, v20
	v_lshlrev_b64 v[20:21], v22, v[146:147]
	v_min_u32_e32 v20, 1, v20
	v_or_b32_e32 v20, v21, v20
	v_cvt_f32_i32_e32 v20, v20
	v_sub_u32_e32 v21, 32, v22
	v_mad_i64_i32 v[18:19], s[14:15], v161, s5, v[148:149]
	v_ldexp_f32 v20, v20, v21
	v_fmamk_f32 v20, v20, 0x32000000, v216
	v_rsq_f32_e32 v20, v20
	v_lshl_add_u64 v[18:19], v[18:19], 0, v[150:151]
	s_mov_b64 s[14:15], -1
	v_pk_fma_f32 v[14:15], v[14:15], v[20:21], v[94:95] op_sel_hi:[1,0,1]
	v_pk_fma_f32 v[16:17], v[16:17], v[20:21], v[96:97] op_sel_hi:[1,0,1]
	v_pk_fma_f32 v[10:11], v[10:11], v[20:21], v[90:91] op_sel_hi:[1,0,1]
	v_pk_fma_f32 v[12:13], v[12:13], v[20:21], v[92:93] op_sel_hi:[1,0,1]
	v_pk_fma_f32 v[6:7], v[6:7], v[20:21], v[86:87] op_sel_hi:[1,0,1]
	v_pk_fma_f32 v[8:9], v[8:9], v[20:21], v[88:89] op_sel_hi:[1,0,1]
	v_pk_fma_f32 v[2:3], v[2:3], v[20:21], v[82:83] op_sel_hi:[1,0,1]
	v_pk_fma_f32 v[4:5], v[4:5], v[20:21], v[84:85] op_sel_hi:[1,0,1]
	v_pk_mul_f32 v[20:21], v[16:17], s[16:17] op_sel_hi:[1,0]
	v_pk_mul_f32 v[22:23], v[14:15], s[16:17] op_sel_hi:[1,0]
	v_exp_f32_e32 v20, v20
	v_exp_f32_e32 v22, v22
	v_exp_f32_e32 v23, v23
	v_exp_f32_e32 v21, v21
	v_pk_add_f32 v[22:23], v[22:23], 1.0 op_sel_hi:[1,0]
	v_pk_add_f32 v[20:21], v[20:21], 1.0 op_sel_hi:[1,0]
	v_rcp_f32_e32 v22, v22
	v_rcp_f32_e32 v23, v23
	v_rcp_f32_e32 v20, v20
	v_rcp_f32_e32 v21, v21
	v_pk_mul_f32 v[14:15], v[14:15], v[22:23]
	s_nop 0
	v_pk_mul_f32 v[6:7], v[6:7], v[14:15]
	v_pk_mul_f32 v[16:17], v[16:17], v[20:21]
	v_pk_mul_f32 v[14:15], v[12:13], s[16:17] op_sel_hi:[1,0]
	v_pk_mul_f32 v[8:9], v[8:9], v[16:17]
	v_pk_mul_f32 v[16:17], v[10:11], s[16:17] op_sel_hi:[1,0]
	v_exp_f32_e32 v14, v14
	v_exp_f32_e32 v16, v16
	v_exp_f32_e32 v17, v17
	v_exp_f32_e32 v15, v15
	v_pk_add_f32 v[16:17], v[16:17], 1.0 op_sel_hi:[1,0]
	v_pk_add_f32 v[14:15], v[14:15], 1.0 op_sel_hi:[1,0]
	v_rcp_f32_e32 v16, v16
	v_rcp_f32_e32 v17, v17
	v_rcp_f32_e32 v14, v14
	v_rcp_f32_e32 v15, v15
	v_pk_mul_f32 v[10:11], v[10:11], v[16:17]
	v_pk_mul_f32 v[12:13], v[12:13], v[14:15]
	s_nop 0
	v_pk_mul_f32 v[12:13], v[4:5], v[12:13]
	v_pk_mul_f32 v[4:5], v[2:3], v[10:11]
	v_cvt_pk_bf16_f32 v2, v6, v7
	v_cvt_pk_bf16_f32 v3, v8, v9
	s_nop 0
	v_cvt_pk_bf16_f32 v4, v4, v5
	v_cvt_pk_bf16_f32 v5, v12, v13
	global_store_dwordx4 v[18:19], v[2:5], off nt
	s_cbranch_vccnz .LBB0_630
	s_andn2_b64 vcc, exec, s[0:1]
	s_cbranch_vccnz .LBB0_629
	s_barrier
	s_branch .LBB0_629
